# attention softmax: cross-half max/sum exchange via v_permlane32_swap instead of ds_bpermute
# speedup vs baseline: 1.0265x; 1.0013x over previous
.LBB0_407:
.LBB0_409:
	s_cmp_ge_i32 s8, s27
	s_cbranch_scc1 .LBB0_413
	s_mul_hi_u32 s8, s8, 0xaaaaaaab
	s_lshr_b32 s8, s8, 1
	s_mul_i32 s8, s8, 0xfffe1400
	s_add_i32 s8, s28, s8
	v_add_u32_e32 v175, s8, v174
	ds_read_b128 v[176:179], v175
	ds_read_b128 v[180:183], v175 offset:32
	ds_read_b128 v[184:187], v175 offset:20992
	ds_read_b128 v[188:191], v175 offset:21024
	ds_read_b128 v[220:223], v175 offset:64
	ds_read_b128 v[224:227], v175 offset:21056
	ds_read_b128 v[228:231], v175 offset:96
	ds_read_b128 v[232:235], v175 offset:21088
	ds_read_b128 v[236:239], v175 offset:128
	ds_read_b128 v[240:243], v175 offset:21120
	s_mov_b32 s8, 0xf149f2ca
	s_waitcnt vmcnt(19) lgkmcnt(9)
	v_mfma_f32_32x32x16_bf16 v[18:33], v[176:179], v[34:37], 0
	ds_read_b128 v[176:179], v175 offset:160
	s_waitcnt vmcnt(18) lgkmcnt(9)
	v_mfma_f32_32x32x16_bf16 v[18:33], v[180:183], v[38:41], v[18:33]
	ds_read_b128 v[180:183], v175 offset:21152
	s_waitcnt lgkmcnt(9)
	v_mfma_f32_32x32x16_bf16 v[2:17], v[184:187], v[34:37], 0
	ds_read_b128 v[184:187], v175 offset:192
	s_waitcnt lgkmcnt(9)
	v_mfma_f32_32x32x16_bf16 v[2:17], v[188:191], v[38:41], v[2:17]
	ds_read_b128 v[188:191], v175 offset:21184
	s_waitcnt vmcnt(17) lgkmcnt(9)
	v_mfma_f32_32x32x16_bf16 v[18:33], v[220:223], v[42:45], v[18:33]
	ds_read_b128 v[220:223], v175 offset:224
	s_waitcnt lgkmcnt(9)
	v_mfma_f32_32x32x16_bf16 v[2:17], v[224:227], v[42:45], v[2:17]
	ds_read_b128 v[224:227], v175 offset:21216
	s_waitcnt vmcnt(16) lgkmcnt(9)
	v_mfma_f32_32x32x16_bf16 v[18:33], v[228:231], v[46:49], v[18:33]
	ds_read_b128 v[228:231], v175 offset:256
	s_waitcnt lgkmcnt(9)
	v_mfma_f32_32x32x16_bf16 v[2:17], v[232:235], v[46:49], v[2:17]
	ds_read_b128 v[232:235], v175 offset:21248
	s_waitcnt vmcnt(15) lgkmcnt(9)
	v_mfma_f32_32x32x16_bf16 v[18:33], v[236:239], v[50:53], v[18:33]
	ds_read_b128 v[236:239], v175 offset:288
	s_waitcnt lgkmcnt(9)
	v_mfma_f32_32x32x16_bf16 v[2:17], v[240:243], v[50:53], v[2:17]
	ds_read_b128 v[240:243], v175 offset:21280
	s_waitcnt vmcnt(14) lgkmcnt(9)
	v_mfma_f32_32x32x16_bf16 v[18:33], v[176:179], v[54:57], v[18:33]
	ds_read_b128 v[176:179], v175 offset:320
	s_waitcnt lgkmcnt(9)
	v_mfma_f32_32x32x16_bf16 v[2:17], v[180:183], v[54:57], v[2:17]
	ds_read_b128 v[180:183], v175 offset:21312
	s_waitcnt vmcnt(13) lgkmcnt(9)
	v_mfma_f32_32x32x16_bf16 v[18:33], v[184:187], v[58:61], v[18:33]
	ds_read_b128 v[184:187], v175 offset:352
	s_waitcnt lgkmcnt(9)
	v_mfma_f32_32x32x16_bf16 v[2:17], v[188:191], v[58:61], v[2:17]
	ds_read_b128 v[188:191], v175 offset:21344
	s_waitcnt vmcnt(12) lgkmcnt(9)
	v_mfma_f32_32x32x16_bf16 v[18:33], v[220:223], v[62:65], v[18:33]
	ds_read_b128 v[220:223], v175 offset:384
	s_waitcnt lgkmcnt(9)
	v_mfma_f32_32x32x16_bf16 v[2:17], v[224:227], v[62:65], v[2:17]
	ds_read_b128 v[224:227], v175 offset:21376
	s_waitcnt vmcnt(11) lgkmcnt(9)
	v_mfma_f32_32x32x16_bf16 v[18:33], v[228:231], v[66:69], v[18:33]
	ds_read_b128 v[228:231], v175 offset:416
	s_waitcnt lgkmcnt(9)
	v_mfma_f32_32x32x16_bf16 v[2:17], v[232:235], v[66:69], v[2:17]
	ds_read_b128 v[232:235], v175 offset:21408
	s_waitcnt vmcnt(10) lgkmcnt(9)
	v_mfma_f32_32x32x16_bf16 v[18:33], v[236:239], v[70:73], v[18:33]
	ds_read_b128 v[236:239], v175 offset:448
	s_waitcnt lgkmcnt(9)
	v_mfma_f32_32x32x16_bf16 v[2:17], v[240:243], v[70:73], v[2:17]
	ds_read_b128 v[240:243], v175 offset:21440
	s_waitcnt vmcnt(9) lgkmcnt(9)
	v_mfma_f32_32x32x16_bf16 v[18:33], v[176:179], v[74:77], v[18:33]
	ds_read_b128 v[176:179], v175 offset:480
	s_waitcnt lgkmcnt(9)
	v_mfma_f32_32x32x16_bf16 v[2:17], v[180:183], v[74:77], v[2:17]
	ds_read_b128 v[180:183], v175 offset:21472
	s_waitcnt vmcnt(8) lgkmcnt(9)
	v_mfma_f32_32x32x16_bf16 v[18:33], v[184:187], v[78:81], v[18:33]
	ds_read_b128 v[184:187], v175 offset:512
	s_waitcnt lgkmcnt(9)
	v_mfma_f32_32x32x16_bf16 v[2:17], v[188:191], v[78:81], v[2:17]
	ds_read_b128 v[188:191], v175 offset:21504
	s_waitcnt vmcnt(7) lgkmcnt(9)
	v_mfma_f32_32x32x16_bf16 v[18:33], v[220:223], v[82:85], v[18:33]
	ds_read_b128 v[220:223], v175 offset:544
	s_waitcnt lgkmcnt(9)
	v_mfma_f32_32x32x16_bf16 v[2:17], v[224:227], v[82:85], v[2:17]
	ds_read_b128 v[224:227], v175 offset:21536
	s_waitcnt vmcnt(6) lgkmcnt(9)
	v_mfma_f32_32x32x16_bf16 v[18:33], v[228:231], v[86:89], v[18:33]
	ds_read_b128 v[228:231], v175 offset:576
	s_waitcnt lgkmcnt(9)
	v_mfma_f32_32x32x16_bf16 v[2:17], v[232:235], v[86:89], v[2:17]
	ds_read_b128 v[232:235], v175 offset:608
	s_waitcnt vmcnt(5) lgkmcnt(9)
	v_mfma_f32_32x32x16_bf16 v[18:33], v[236:239], v[90:93], v[18:33]
	ds_read_b128 v[236:239], v175 offset:21568
	s_waitcnt lgkmcnt(9)
	v_mfma_f32_32x32x16_bf16 v[2:17], v[240:243], v[90:93], v[2:17]
	ds_read_b128 v[240:243], v175 offset:21600
	s_waitcnt vmcnt(4) lgkmcnt(9)
	v_mfma_f32_32x32x16_bf16 v[18:33], v[176:179], v[94:97], v[18:33]
	s_waitcnt lgkmcnt(8)
	v_mfma_f32_32x32x16_bf16 v[2:17], v[180:183], v[94:97], v[2:17]
	s_waitcnt vmcnt(3) lgkmcnt(7)
	v_mfma_f32_32x32x16_bf16 v[18:33], v[184:187], v[98:101], v[18:33]
	s_waitcnt lgkmcnt(6)
	v_mfma_f32_32x32x16_bf16 v[2:17], v[188:191], v[98:101], v[2:17]
	s_waitcnt vmcnt(2) lgkmcnt(5)
	v_mfma_f32_32x32x16_bf16 v[18:33], v[220:223], v[102:105], v[18:33]
	s_waitcnt lgkmcnt(4)
	v_mfma_f32_32x32x16_bf16 v[2:17], v[224:227], v[102:105], v[2:17]
	s_waitcnt vmcnt(1) lgkmcnt(3)
	v_mfma_f32_32x32x16_bf16 v[18:33], v[228:231], v[106:109], v[18:33]
	s_waitcnt vmcnt(0) lgkmcnt(2)
	v_mfma_f32_32x32x16_bf16 v[18:33], v[232:235], v[110:113], v[18:33]
	s_waitcnt lgkmcnt(1)
	v_mfma_f32_32x32x16_bf16 v[2:17], v[236:239], v[106:109], v[2:17]
	s_nop 9
	v_max3_f32 v175, v18, s8, v19
	v_max3_f32 v175, v175, v20, v21
	v_max3_f32 v175, v175, v22, v23
	v_max3_f32 v175, v175, v24, v25
	v_max3_f32 v175, v175, v26, v27
	v_max3_f32 v175, v175, v28, v29
	v_max3_f32 v175, v175, v30, v31
	s_waitcnt lgkmcnt(0)
	v_mfma_f32_32x32x16_bf16 v[2:17], v[240:243], v[110:113], v[2:17]
	v_max3_f32 v175, v175, v32, v33
	v_xor_b32_e32 v176, 32, v192
	v_add_u32_e32 v177, 64, v193
	v_cmp_lt_i32_e32 vcc, v176, v177
	s_and_b32 s8, s29, 4
	s_or_b32 s8, s8, s91
	v_cndmask_b32_e32 v176, v192, v176, vcc
	s_nop 4
	v_max3_f32 v175, v175, v2, v3
	v_max3_f32 v175, v175, v4, v5
	v_max3_f32 v175, v175, v6, v7
	v_max3_f32 v175, v175, v8, v9
	v_max3_f32 v175, v175, v10, v11
	v_max3_f32 v175, v175, v12, v13
	v_max3_f32 v175, v175, v14, v15
	v_max3_f32 v175, v175, v16, v17
	v_lshlrev_b32_e32 v176, 2, v176
	v_mov_b32_e32 v177, v175
	s_mulk_i32 s8, 0x1080
	s_add_i32 s8, s8, 0
	s_add_i32 s8, s8, 0x1ec00
	v_permlane32_swap_b32_e32 v177, v175
	v_max3_f32 v175, v165, v175, v177
	v_sub_f32_e32 v177, v175, v165
	v_cmp_lt_f32_e32 vcc, 8.0, v177
	s_nop 1
	v_cndmask_b32_e32 v175, v165, v175, vcc
	v_sub_f32_e32 v18, v18, v175
	v_exp_f32_e32 v18, v18
	v_sub_f32_e32 v19, v19, v175
	v_exp_f32_e32 v19, v19
	v_sub_f32_e32 v20, v20, v175
	v_exp_f32_e32 v20, v20
	v_sub_f32_e32 v21, v21, v175
	v_exp_f32_e32 v21, v21
	v_sub_f32_e32 v22, v22, v175
	v_add_f32_e32 v177, 0, v18
	v_exp_f32_e32 v22, v22
	v_sub_f32_e32 v23, v23, v175
	v_add_f32_e32 v177, v177, v19
	v_exp_f32_e32 v23, v23
	v_sub_f32_e32 v24, v24, v175
	v_add_f32_e32 v177, v177, v20
	v_exp_f32_e32 v24, v24
	v_sub_f32_e32 v25, v25, v175
	v_add_f32_e32 v177, v177, v21
	v_exp_f32_e32 v25, v25
	v_sub_f32_e32 v26, v26, v175
	v_add_f32_e32 v177, v177, v22
	v_exp_f32_e32 v26, v26
	v_sub_f32_e32 v27, v27, v175
	v_add_f32_e32 v177, v177, v23
	v_exp_f32_e32 v27, v27
	v_sub_f32_e32 v28, v28, v175
	v_add_f32_e32 v177, v177, v24
	v_exp_f32_e32 v28, v28
	v_sub_f32_e32 v29, v29, v175
	v_add_f32_e32 v177, v177, v25
	v_exp_f32_e32 v29, v29
	v_sub_f32_e32 v30, v30, v175
	v_add_f32_e32 v177, v177, v26
	v_exp_f32_e32 v30, v30
	v_sub_f32_e32 v31, v31, v175
	v_add_f32_e32 v177, v177, v27
	v_exp_f32_e32 v31, v31
	v_sub_f32_e32 v32, v32, v175
	v_add_f32_e32 v177, v177, v28
	v_exp_f32_e32 v32, v32
	v_sub_f32_e32 v33, v33, v175
	v_add_f32_e32 v177, v177, v29
	v_exp_f32_e32 v33, v33
	v_sub_f32_e32 v2, v2, v175
	v_add_f32_e32 v177, v177, v30
	v_exp_f32_e32 v178, v2
	v_sub_f32_e32 v2, v3, v175
	v_add_f32_e32 v177, v177, v31
	v_exp_f32_e32 v179, v2
	v_sub_f32_e32 v2, v4, v175
	v_add_f32_e32 v177, v177, v32
	v_exp_f32_e32 v180, v2
	v_sub_f32_e32 v2, v5, v175
	v_add_f32_e32 v177, v177, v33
	v_exp_f32_e32 v5, v2
	v_sub_f32_e32 v3, v6, v175
	v_add_f32_e32 v2, v177, v178
	v_exp_f32_e32 v177, v3
	v_sub_f32_e32 v3, v7, v175
	v_add_f32_e32 v2, v2, v179
	v_exp_f32_e32 v181, v3
	v_sub_f32_e32 v3, v8, v175
	v_add_f32_e32 v2, v2, v180
	v_exp_f32_e32 v182, v3
	v_sub_f32_e32 v3, v9, v175
	v_add_f32_e32 v2, v2, v5
	v_exp_f32_e32 v183, v3
	v_sub_f32_e32 v3, v10, v175
	v_add_f32_e32 v2, v2, v177
	v_exp_f32_e32 v10, v3
	v_sub_f32_e32 v3, v11, v175
	v_add_f32_e32 v2, v2, v181
	v_exp_f32_e32 v11, v3
	v_sub_f32_e32 v3, v12, v175
	v_add_f32_e32 v2, v2, v182
	v_exp_f32_e32 v12, v3
	v_sub_f32_e32 v3, v13, v175
	v_add_f32_e32 v2, v2, v183
	v_exp_f32_e32 v13, v3
	v_sub_f32_e32 v3, v14, v175
	v_add_f32_e32 v2, v2, v10
	v_exp_f32_e32 v14, v3
	v_sub_f32_e32 v3, v15, v175
	v_add_f32_e32 v2, v2, v11
	v_exp_f32_e32 v15, v3
	v_sub_f32_e32 v3, v16, v175
	v_add_f32_e32 v2, v2, v12
	v_exp_f32_e32 v16, v3
	v_sub_f32_e32 v3, v17, v175
	v_add_f32_e32 v2, v2, v13
	v_exp_f32_e32 v17, v3
	v_add_f32_e32 v2, v2, v14
	v_add_f32_e32 v2, v2, v15
	v_add_f32_e32 v2, v2, v16
	v_add_f32_e32 v2, v2, v17
	v_sub_f32_e32 v165, v165, v175
	v_mov_b32_e32 v4, v2
	v_exp_f32_e32 v3, v165
	v_add_u32_e32 v165, s8, v169
	v_permlane32_swap_b32_e32 v4, v2
	v_cvt_pk_bf16_f32 v6, v18, v19
	v_cvt_pk_bf16_f32 v7, v20, v21
	v_cvt_pk_bf16_f32 v8, v22, v23
	v_cvt_pk_bf16_f32 v9, v24, v25
	ds_write_b128 v165, v[6:9]
	v_cvt_pk_bf16_f32 v6, v26, v27
	v_cvt_pk_bf16_f32 v7, v28, v29
	v_cvt_pk_bf16_f32 v8, v30, v31
	v_cvt_pk_bf16_f32 v9, v32, v33
	ds_write_b128 v165, v[6:9] offset:1024
	v_cvt_pk_bf16_f32 v6, v178, v179
	v_cvt_pk_bf16_f32 v7, v180, v5
	v_cvt_pk_bf16_f32 v8, v177, v181
	v_cvt_pk_bf16_f32 v9, v182, v183
	ds_write_b128 v165, v[6:9] offset:2048
	v_cvt_pk_bf16_f32 v6, v10, v11
	v_cvt_pk_bf16_f32 v7, v12, v13
	v_cvt_pk_bf16_f32 v8, v14, v15
	v_cvt_pk_bf16_f32 v9, v16, v17
	ds_write_b128 v165, v[6:9] offset:3072
	s_and_saveexec_b64 s[16:17], s[4:5]
	v_add_u32_e32 v5, s8, v171
	ds_write_b32 v5, v3 offset:4096
	s_or_b64 exec, exec, s[16:17]
	s_waitcnt lgkmcnt(4)
	v_add_f32_e32 v2, v2, v4
	v_fmac_f32_e32 v2, v0, v3
	v_mov_b32_e32 v0, v2
	s_branch .LBB0_414
